# mixer prep token loop rewritten: scalar row decode, all loads of a token issued together, 12 wave reductions batched
# speedup vs baseline: 1.0399x; 1.0191x over previous
; DI void phase_prep(const P& p, int l, int boff, int geff) {
;     ...
;   const float* qn = p.in[I_QNORM] + l * 384;
;   const float* kvn = p.in[I_KVNORM] + l * 256;
;   const float gq = p.in[I_GQN][l * 64 + lane], gk = p.in[I_GKN][l * 64 + lane];
;   for (int row = gw; row < TA; row += nw) {
;     const bool lat = row < TL;
;     const int b = lat ? (row >> 12) : ((row - TL) >> 8);
;     const int srow = srow_of(row);
;     const int tpos = row & 4095;
;     {
;       h16* cq = cqkv + (size_t)row * 640;
;       float x[6], ss = 0.f;
; #pragma unroll
;       for (int i = 0; i < 6; ++i) { x[i] = (float)cq[lane + 64 * i]; ss += x[i] * x[i]; }
;       ss = wave_sum(ss);
;       float rstd = rsqrtf(ss * (1.f / 384.f) + EPS);
; #pragma unroll
;       for (int i = 0; i < 6; ++i) cq[lane + 64 * i] = (h16)(x[i] * rstd * qn[lane + 64 * i]);
;       h16* ck = cq + 384;
;       float y[4]; ss = 0.f;
; #pragma unroll
;       for (int i = 0; i < 4; ++i) { y[i] = (float)ck[lane + 64 * i]; ss += y[i] * y[i]; }
;       ss = wave_sum(ss);
;       rstd = rsqrtf(ss * (1.f / 256.f) + EPS);
; #pragma unroll
;       for (int i = 0; i < 4; ++i) ck[lane + 64 * i] = (h16)(y[i] * rstd * kvn[lane + 64 * i]);
;     }
;     if (lat && lane < 16) {
;       h16* kr = krot + (size_t)srow * 32;
;       float x1 = (float)kr[lane], x2 = (float)kr[lane + 16];
;       f32x2 cs = rm[tpos * 16 + lane];
;       kr[lane] = (h16)(x1 * cs.x - x2 * cs.y);
;       kr[lane + 16] = (h16)(x1 * cs.y + x2 * cs.x);
;     }
;     f32x2 cs; cs.x = 1.f; cs.y = 0.f;
;     if (lat) cs = rg[tpos * 32 + (lane & 31)];
; #pragma unroll
;     for (int hq = 0; hq < 8; ++hq) {
;       h16* q = Qg + ((size_t)(b * 8 + hq) * SA + (srow - b * SA)) * 64;
;       float x = (float)q[lane];
;       float ss = wave_sum(x * x);
;       x = x * rsqrtf(ss * (1.f / 64.f) + EPS) * gq;
;       float o = shx(x, 32);
;       float rr = lane < 32 ? (x * cs.x - o * cs.y) : (o * cs.y + x * cs.x);
;       q[lane] = (h16)(rr * (0.125f * LOG2E));
;     }
; #pragma unroll
;     for (int kh = 0; kh < 2; ++kh) {
;       h16* k = Kg + ((size_t)(b * 2 + kh) * SA + (srow - b * SA)) * 64;
;       float x = (float)k[lane];
;       float ss = wave_sum(x * x);
;       x = x * rsqrtf(ss * (1.f / 64.f) + EPS) * gk;
;       float o = shx(x, 32);
;       float rr = lane < 32 ? (x * cs.x - o * cs.y) : (o * cs.y + x * cs.x);
;       k[lane] = (h16)rr;
;     }
.LBB0_2048:
	global_load_dword v48, v[8:9], off
	global_load_dword v49, v[8:9], off offset:256
	global_load_dword v50, v[8:9], off offset:512
	global_load_dword v51, v[8:9], off offset:768
	global_load_dword v52, v[8:9], off offset:1024
	global_load_dword v53, v[8:9], off offset:1280
	global_load_dword v54, v[10:11], off
	global_load_dword v55, v[10:11], off offset:256
	global_load_dword v56, v[10:11], off offset:512
	global_load_dword v57, v[10:11], off offset:768
	v_lshlrev_b32_e32 v58, 1, v27
	v_lshlrev_b32_e32 v59, 3, v30
	v_lshlrev_b32_e32 v60, 3, v27
	v_lshlrev_b32_e32 v61, 2, v27
	v_xor_b32_e32 v61, 0x80, v61
	v_mov_b32_e32 v80, v58
	v_add_u32_e32 v81, 0x88000, v58
	v_add_u32_e32 v82, 0x110000, v58
	v_add_u32_e32 v83, 0x198000, v58
	v_add_u32_e32 v84, 0x220000, v58
	v_add_u32_e32 v85, 0x2a8000, v58
	v_add_u32_e32 v86, 0x330000, v58
	v_add_u32_e32 v87, 0x3b8000, v58
	s_add_u32 s50, s48, 0xf4ec000
	s_addc_u32 s51, s49, 0
	s_add_u32 s52, s48, 0x2f4c000
	s_addc_u32 s53, s49, 0
	s_add_u32 s54, s48, 0x1afec000
	s_addc_u32 s55, s49, 0
	s_add_u32 s56, s48, 0x1d1ec000
	s_addc_u32 s57, s49, 0
	s_mov_b32 s58, 0x3b2aaaab
	s_mov_b32 s59, 0x3e38aa3b
.Lprep_loop:
	v_readfirstlane_b32 s0, v26
	s_nop 3
	v_add_u32_e32 v26, s2, v26
	s_add_i32 s46, s0, s2
	s_lshr_b32 s10, s0, 12
	s_and_b32 s40, s0, 0xfff
	s_sub_u32 s1, s0, 0x8000
	s_lshr_b32 s41, s1, 8
	s_and_b32 s1, s1, 0xff
	s_add_u32 s1, s1, 0x1000
	s_cmp_lt_u32 s0, 0x8000
	s_cselect_b32 s10, s10, s41
	s_cselect_b32 s11, s40, s1
	s_cselect_b64 s[42:43], -1, 0
	s_mul_i32 s12, s0, 0x500
	s_mul_hi_u32 s13, s0, 0x500
	s_add_u32 s12, s12, s50
	s_addc_u32 s13, s13, s51
	s_mul_i32 s41, s10, 0x1100
	s_add_u32 s41, s41, s11
	s_lshl_b32 s16, s41, 6
	s_add_u32 s16, s16, s52
	s_addc_u32 s17, s53, 0
	s_lshl_b32 s18, s40, 7
	s_add_u32 s18, s18, s44
	s_addc_u32 s19, s45, 0
	s_lshl_b32 s20, s40, 8
	s_add_u32 s20, s20, s6
	s_addc_u32 s21, s7, 0
	s_mul_i32 s1, s10, 0x8800
	s_add_u32 s1, s1, s11
	s_lshl_b32 s22, s1, 7
	s_add_u32 s22, s22, s54
	s_addc_u32 s23, s55, 0
	s_mul_i32 s1, s10, 0x2200
	s_add_u32 s1, s1, s11
	s_lshl_b32 s34, s1, 7
	s_add_u32 s34, s34, s56
	s_addc_u32 s35, s57, 0
	global_load_ushort v88, v58, s[12:13]
	global_load_ushort v89, v58, s[12:13] offset:128
	global_load_ushort v90, v58, s[12:13] offset:256
	global_load_ushort v91, v58, s[12:13] offset:384
	global_load_ushort v92, v58, s[12:13] offset:512
	global_load_ushort v93, v58, s[12:13] offset:640
	global_load_ushort v94, v58, s[12:13] offset:768
	global_load_ushort v95, v58, s[12:13] offset:896
	global_load_ushort v96, v58, s[12:13] offset:1024
	global_load_ushort v97, v58, s[12:13] offset:1152
	global_load_ushort v104, v80, s[22:23]
	global_load_ushort v105, v81, s[22:23]
	global_load_ushort v106, v82, s[22:23]
	global_load_ushort v107, v83, s[22:23]
	global_load_ushort v108, v84, s[22:23]
	global_load_ushort v109, v85, s[22:23]
	global_load_ushort v110, v86, s[22:23]
	global_load_ushort v111, v87, s[22:23]
	global_load_ushort v112, v80, s[34:35]
	global_load_ushort v113, v81, s[34:35]
	v_mov_b32_e32 v102, 1.0
	v_mov_b32_e32 v103, 0
	s_and_b64 vcc, exec, s[42:43]
	s_cbranch_vccz .Lprep_ld_done
	global_load_dwordx2 v[102:103], v59, s[20:21]
	v_cmp_gt_u32_e64 s[8:9], 16, v27
	s_nop 1
	s_and_saveexec_b64 s[8:9], s[8:9]
	global_load_ushort v98, v58, s[16:17]
	global_load_ushort v99, v58, s[16:17] offset:32
	global_load_dwordx2 v[100:101], v60, s[18:19]
	s_or_b64 exec, exec, s[8:9]
.Lprep_ld_done:
	s_waitcnt vmcnt(0)
	v_cvt_f32_f16_e32 v14, v88
	v_cvt_f32_f16_e32 v15, v89
	v_cvt_f32_f16_e32 v16, v90
	v_cvt_f32_f16_e32 v17, v91
	v_cvt_f32_f16_e32 v18, v92
	v_cvt_f32_f16_e32 v19, v93
	v_cvt_f32_f16_e32 v20, v94
	v_cvt_f32_f16_e32 v21, v95
	v_cvt_f32_f16_e32 v22, v96
	v_cvt_f32_f16_e32 v23, v97
	v_cvt_f32_f16_e32 v114, v104
	v_cvt_f32_f16_e32 v115, v105
	v_cvt_f32_f16_e32 v116, v106
	v_cvt_f32_f16_e32 v117, v107
	v_cvt_f32_f16_e32 v118, v108
	v_cvt_f32_f16_e32 v119, v109
	v_cvt_f32_f16_e32 v120, v110
	v_cvt_f32_f16_e32 v121, v111
	v_cvt_f32_f16_e32 v122, v112
	v_cvt_f32_f16_e32 v123, v113
	v_mul_f32_e32 v24, v15, v15
	v_mul_f32_e32 v25, v21, v21
	v_mul_f32_e32 v31, v114, v114
	v_mul_f32_e32 v32, v115, v115
	v_mul_f32_e32 v33, v116, v116
	v_mul_f32_e32 v34, v117, v117
	v_mul_f32_e32 v35, v118, v118
	v_mul_f32_e32 v36, v119, v119
	v_mul_f32_e32 v37, v120, v120
	v_mul_f32_e32 v38, v121, v121
	v_mul_f32_e32 v39, v122, v122
	v_mul_f32_e32 v40, v123, v123
	v_fma_f32 v24, v14, v14, v24
	v_fma_f32 v25, v20, v20, v25
	v_mov_b32_dpp v31, v31 quad_perm:[1,0,3,2] row_mask:0xf bank_mask:0xf bound_ctrl:1
	v_mov_b32_dpp v32, v32 quad_perm:[1,0,3,2] row_mask:0xf bank_mask:0xf bound_ctrl:1
	v_mov_b32_dpp v33, v33 quad_perm:[1,0,3,2] row_mask:0xf bank_mask:0xf bound_ctrl:1
	v_mov_b32_dpp v34, v34 quad_perm:[1,0,3,2] row_mask:0xf bank_mask:0xf bound_ctrl:1
	v_mov_b32_dpp v35, v35 quad_perm:[1,0,3,2] row_mask:0xf bank_mask:0xf bound_ctrl:1
	v_mov_b32_dpp v36, v36 quad_perm:[1,0,3,2] row_mask:0xf bank_mask:0xf bound_ctrl:1
	v_mov_b32_dpp v37, v37 quad_perm:[1,0,3,2] row_mask:0xf bank_mask:0xf bound_ctrl:1
	v_mov_b32_dpp v38, v38 quad_perm:[1,0,3,2] row_mask:0xf bank_mask:0xf bound_ctrl:1
	v_mov_b32_dpp v39, v39 quad_perm:[1,0,3,2] row_mask:0xf bank_mask:0xf bound_ctrl:1
	v_mov_b32_dpp v40, v40 quad_perm:[1,0,3,2] row_mask:0xf bank_mask:0xf bound_ctrl:1
	v_fma_f32 v24, v16, v16, v24
	v_fma_f32 v25, v22, v22, v25
	v_fma_f32 v24, v17, v17, v24
	v_fma_f32 v25, v23, v23, v25
	v_fma_f32 v31, v114, v114, v31
	v_fma_f32 v32, v115, v115, v32
	v_fma_f32 v33, v116, v116, v33
	v_fma_f32 v34, v117, v117, v34
	v_fma_f32 v35, v118, v118, v35
	v_fma_f32 v36, v119, v119, v36
; DI float wave_sum(float v) {
;   v += __int_as_float(__builtin_amdgcn_mov_dpp(__float_as_int(v), 0xB1, 0xF, 0xF, true));
;   v += __int_as_float(__builtin_amdgcn_mov_dpp(__float_as_int(v), 0x4E, 0xF, 0xF, true));
;   v += __int_as_float(__builtin_amdgcn_mov_dpp(__float_as_int(v), 0x141, 0xF, 0xF, true));
;   v += __int_as_float(__builtin_amdgcn_mov_dpp(__float_as_int(v), 0x140, 0xF, 0xF, true));
;   v += __int_as_float(__builtin_amdgcn_ds_swizzle(__float_as_int(v), 0x401F));
;   return x32_sum(v);
; }
; DI void phase_prep(const P& p, int l, int boff, int geff) {
;     ...
;       for (int i = 0; i < 6; ++i) { x[i] = (float)cq[lane + 64 * i]; ss += x[i] * x[i]; }
;       ss = wave_sum(ss);
;       float rstd = rsqrtf(ss * (1.f / 384.f) + EPS);
; #pragma unroll
;       for (int i = 0; i < 6; ++i) cq[lane + 64 * i] = (h16)(x[i] * rstd * qn[lane + 64 * i]);
;       h16* ck = cq + 384;
;       float y[4]; ss = 0.f;
; #pragma unroll
;       for (int i = 0; i < 4; ++i) { y[i] = (float)ck[lane + 64 * i]; ss += y[i] * y[i]; }
;       ss = wave_sum(ss);
;       rstd = rsqrtf(ss * (1.f / 256.f) + EPS);
; #pragma unroll
;       for (int i = 0; i < 4; ++i) ck[lane + 64 * i] = (h16)(y[i] * rstd * kvn[lane + 64 * i]);
;     }
;     if (lat && lane < 16) {
;       h16* kr = krot + (size_t)srow * 32;
;       float x1 = (float)kr[lane], x2 = (float)kr[lane + 16];
;       f32x2 cs = rm[tpos * 16 + lane];
;       kr[lane] = (h16)(x1 * cs.x - x2 * cs.y);
;       kr[lane + 16] = (h16)(x1 * cs.y + x2 * cs.x);
;     }
;     f32x2 cs; cs.x = 1.f; cs.y = 0.f;
;     if (lat) cs = rg[tpos * 32 + (lane & 31)];
; #pragma unroll
;     for (int hq = 0; hq < 8; ++hq) {
;       h16* q = Qg + ((size_t)(b * 8 + hq) * SA + (srow - b * SA)) * 64;
;       float x = (float)q[lane];
;       float ss = wave_sum(x * x);
;       x = x * rsqrtf(ss * (1.f / 64.f) + EPS) * gq;
;       float o = shx(x, 32);
;       float rr = lane < 32 ? (x * cs.x - o * cs.y) : (o * cs.y + x * cs.x);
;       q[lane] = (h16)(rr * (0.125f * LOG2E));
;     }
; #pragma unroll
;     for (int kh = 0; kh < 2; ++kh) {
;       h16* k = Kg + ((size_t)(b * 2 + kh) * SA + (srow - b * SA)) * 64;
;       float x = (float)k[lane];
;       float ss = wave_sum(x * x);
	v_fma_f32 v37, v120, v120, v37
	v_fma_f32 v38, v121, v121, v38
	v_fma_f32 v39, v122, v122, v39
	v_fma_f32 v40, v123, v123, v40
	v_fma_f32 v24, v18, v18, v24
	v_fma_f32 v24, v19, v19, v24
	s_nop 1
	v_add_f32_dpp v24, v24, v24 quad_perm:[1,0,3,2] row_mask:0xf bank_mask:0xf bound_ctrl:1
	v_add_f32_dpp v25, v25, v25 quad_perm:[1,0,3,2] row_mask:0xf bank_mask:0xf bound_ctrl:1
	v_add_f32_dpp v31, v31, v31 quad_perm:[2,3,0,1] row_mask:0xf bank_mask:0xf bound_ctrl:1
	v_add_f32_dpp v32, v32, v32 quad_perm:[2,3,0,1] row_mask:0xf bank_mask:0xf bound_ctrl:1
	v_add_f32_dpp v33, v33, v33 quad_perm:[2,3,0,1] row_mask:0xf bank_mask:0xf bound_ctrl:1
	v_add_f32_dpp v34, v34, v34 quad_perm:[2,3,0,1] row_mask:0xf bank_mask:0xf bound_ctrl:1
	v_add_f32_dpp v35, v35, v35 quad_perm:[2,3,0,1] row_mask:0xf bank_mask:0xf bound_ctrl:1
	v_add_f32_dpp v36, v36, v36 quad_perm:[2,3,0,1] row_mask:0xf bank_mask:0xf bound_ctrl:1
	v_add_f32_dpp v37, v37, v37 quad_perm:[2,3,0,1] row_mask:0xf bank_mask:0xf bound_ctrl:1
	v_add_f32_dpp v38, v38, v38 quad_perm:[2,3,0,1] row_mask:0xf bank_mask:0xf bound_ctrl:1
	v_add_f32_dpp v39, v39, v39 quad_perm:[2,3,0,1] row_mask:0xf bank_mask:0xf bound_ctrl:1
	v_add_f32_dpp v40, v40, v40 quad_perm:[2,3,0,1] row_mask:0xf bank_mask:0xf bound_ctrl:1
	v_add_f32_dpp v24, v24, v24 quad_perm:[2,3,0,1] row_mask:0xf bank_mask:0xf bound_ctrl:1
	v_add_f32_dpp v25, v25, v25 quad_perm:[2,3,0,1] row_mask:0xf bank_mask:0xf bound_ctrl:1
	v_add_f32_dpp v31, v31, v31 row_half_mirror row_mask:0xf bank_mask:0xf bound_ctrl:1
	v_add_f32_dpp v32, v32, v32 row_half_mirror row_mask:0xf bank_mask:0xf bound_ctrl:1
	v_add_f32_dpp v33, v33, v33 row_half_mirror row_mask:0xf bank_mask:0xf bound_ctrl:1
	v_add_f32_dpp v34, v34, v34 row_half_mirror row_mask:0xf bank_mask:0xf bound_ctrl:1
	v_add_f32_dpp v35, v35, v35 row_half_mirror row_mask:0xf bank_mask:0xf bound_ctrl:1
	v_add_f32_dpp v36, v36, v36 row_half_mirror row_mask:0xf bank_mask:0xf bound_ctrl:1
	v_add_f32_dpp v37, v37, v37 row_half_mirror row_mask:0xf bank_mask:0xf bound_ctrl:1
	v_add_f32_dpp v38, v38, v38 row_half_mirror row_mask:0xf bank_mask:0xf bound_ctrl:1
	v_add_f32_dpp v39, v39, v39 row_half_mirror row_mask:0xf bank_mask:0xf bound_ctrl:1
	v_add_f32_dpp v40, v40, v40 row_half_mirror row_mask:0xf bank_mask:0xf bound_ctrl:1
	v_add_f32_dpp v24, v24, v24 row_half_mirror row_mask:0xf bank_mask:0xf bound_ctrl:1
	v_add_f32_dpp v25, v25, v25 row_half_mirror row_mask:0xf bank_mask:0xf bound_ctrl:1
	v_add_f32_dpp v31, v31, v31 row_mirror row_mask:0xf bank_mask:0xf bound_ctrl:1
	v_add_f32_dpp v32, v32, v32 row_mirror row_mask:0xf bank_mask:0xf bound_ctrl:1
	v_add_f32_dpp v33, v33, v33 row_mirror row_mask:0xf bank_mask:0xf bound_ctrl:1
	v_add_f32_dpp v34, v34, v34 row_mirror row_mask:0xf bank_mask:0xf bound_ctrl:1
	v_add_f32_dpp v35, v35, v35 row_mirror row_mask:0xf bank_mask:0xf bound_ctrl:1
	v_add_f32_dpp v36, v36, v36 row_mirror row_mask:0xf bank_mask:0xf bound_ctrl:1
	v_add_f32_dpp v37, v37, v37 row_mirror row_mask:0xf bank_mask:0xf bound_ctrl:1
	v_add_f32_dpp v38, v38, v38 row_mirror row_mask:0xf bank_mask:0xf bound_ctrl:1
	v_add_f32_dpp v39, v39, v39 row_mirror row_mask:0xf bank_mask:0xf bound_ctrl:1
	v_add_f32_dpp v40, v40, v40 row_mirror row_mask:0xf bank_mask:0xf bound_ctrl:1
	v_add_f32_dpp v24, v24, v24 row_mirror row_mask:0xf bank_mask:0xf bound_ctrl:1
	v_add_f32_dpp v25, v25, v25 row_mirror row_mask:0xf bank_mask:0xf bound_ctrl:1
	ds_swizzle_b32 v124, v24 offset:swizzle(SWAP,16)
	ds_swizzle_b32 v125, v25 offset:swizzle(SWAP,16)
	ds_swizzle_b32 v126, v31 offset:swizzle(SWAP,16)
	ds_swizzle_b32 v127, v32 offset:swizzle(SWAP,16)
	ds_swizzle_b32 v128, v33 offset:swizzle(SWAP,16)
	ds_swizzle_b32 v129, v34 offset:swizzle(SWAP,16)
	ds_swizzle_b32 v62, v35 offset:swizzle(SWAP,16)
	ds_swizzle_b32 v63, v36 offset:swizzle(SWAP,16)
	ds_swizzle_b32 v64, v37 offset:swizzle(SWAP,16)
	ds_swizzle_b32 v41, v38 offset:swizzle(SWAP,16)
	ds_swizzle_b32 v12, v39 offset:swizzle(SWAP,16)
	ds_swizzle_b32 v13, v40 offset:swizzle(SWAP,16)
	s_waitcnt lgkmcnt(11)
	v_add_f32_e32 v24, v24, v124
	s_waitcnt lgkmcnt(10)
	v_add_f32_e32 v25, v25, v125
	s_waitcnt lgkmcnt(9)
	v_add_f32_e32 v31, v31, v126
	s_waitcnt lgkmcnt(8)
	v_add_f32_e32 v32, v32, v127
	s_waitcnt lgkmcnt(7)
	v_add_f32_e32 v33, v33, v128
	s_waitcnt lgkmcnt(6)
	v_add_f32_e32 v34, v34, v129
	s_waitcnt lgkmcnt(5)
	v_add_f32_e32 v35, v35, v62
	s_waitcnt lgkmcnt(4)
	v_add_f32_e32 v36, v36, v63
	s_waitcnt lgkmcnt(3)
	v_add_f32_e32 v37, v37, v64
	s_waitcnt lgkmcnt(2)
	v_add_f32_e32 v38, v38, v41
	s_waitcnt lgkmcnt(1)
	v_add_f32_e32 v39, v39, v12
	s_waitcnt lgkmcnt(0)
; DI void phase_prep(const P& p, int l, int boff, int geff) {
;     ...
;       for (int i = 0; i < 6; ++i) { x[i] = (float)cq[lane + 64 * i]; ss += x[i] * x[i]; }
;       ss = wave_sum(ss);
;       float rstd = rsqrtf(ss * (1.f / 384.f) + EPS);
; #pragma unroll
;       for (int i = 0; i < 6; ++i) cq[lane + 64 * i] = (h16)(x[i] * rstd * qn[lane + 64 * i]);
;       h16* ck = cq + 384;
;       float y[4]; ss = 0.f;
; #pragma unroll
;       for (int i = 0; i < 4; ++i) { y[i] = (float)ck[lane + 64 * i]; ss += y[i] * y[i]; }
;       ss = wave_sum(ss);
;       rstd = rsqrtf(ss * (1.f / 256.f) + EPS);
; #pragma unroll
;       for (int i = 0; i < 4; ++i) ck[lane + 64 * i] = (h16)(y[i] * rstd * kvn[lane + 64 * i]);
;     }
;     if (lat && lane < 16) {
;       h16* kr = krot + (size_t)srow * 32;
;       float x1 = (float)kr[lane], x2 = (float)kr[lane + 16];
;       f32x2 cs = rm[tpos * 16 + lane];
;       kr[lane] = (h16)(x1 * cs.x - x2 * cs.y);
;       kr[lane + 16] = (h16)(x1 * cs.y + x2 * cs.x);
;     }
;     f32x2 cs; cs.x = 1.f; cs.y = 0.f;
;     if (lat) cs = rg[tpos * 32 + (lane & 31)];
; #pragma unroll
;     for (int hq = 0; hq < 8; ++hq) {
;       h16* q = Qg + ((size_t)(b * 8 + hq) * SA + (srow - b * SA)) * 64;
;       float x = (float)q[lane];
;       float ss = wave_sum(x * x);
;       x = x * rsqrtf(ss * (1.f / 64.f) + EPS) * gq;
;       float o = shx(x, 32);
;       float rr = lane < 32 ? (x * cs.x - o * cs.y) : (o * cs.y + x * cs.x);
;       q[lane] = (h16)(rr * (0.125f * LOG2E));
;     }
; #pragma unroll
;     for (int kh = 0; kh < 2; ++kh) {
;       h16* k = Kg + ((size_t)(b * 2 + kh) * SA + (srow - b * SA)) * 64;
;       float x = (float)k[lane];
;       float ss = wave_sum(x * x);
;       x = x * rsqrtf(ss * (1.f / 64.f) + EPS) * gk;
;       float o = shx(x, 32);
;       float rr = lane < 32 ? (x * cs.x - o * cs.y) : (o * cs.y + x * cs.x);
;       k[lane] = (h16)rr;
;     }
;   }
	v_add_f32_e32 v40, v40, v13
	v_mov_b32_e32 v124, v24
	v_mov_b32_e32 v125, v25
	v_mov_b32_e32 v126, v31
	v_mov_b32_e32 v127, v32
	v_mov_b32_e32 v128, v33
	v_mov_b32_e32 v129, v34
	v_mov_b32_e32 v62, v35
	v_mov_b32_e32 v63, v36
	v_mov_b32_e32 v64, v37
	v_mov_b32_e32 v41, v38
	v_mov_b32_e32 v12, v39
	v_mov_b32_e32 v13, v40
	v_permlane32_swap_b32_e32 v24, v124
	v_permlane32_swap_b32_e32 v25, v125
	v_permlane32_swap_b32_e32 v31, v126
	v_permlane32_swap_b32_e32 v32, v127
	v_permlane32_swap_b32_e32 v33, v128
	v_permlane32_swap_b32_e32 v34, v129
	v_permlane32_swap_b32_e32 v35, v62
	v_permlane32_swap_b32_e32 v36, v63
	v_permlane32_swap_b32_e32 v37, v64
	v_permlane32_swap_b32_e32 v38, v41
	v_permlane32_swap_b32_e32 v39, v12
	v_permlane32_swap_b32_e32 v40, v13
	v_add_f32_e32 v24, v24, v124
	v_add_f32_e32 v25, v25, v125
	v_add_f32_e32 v31, v31, v126
	v_add_f32_e32 v32, v32, v127
	v_add_f32_e32 v33, v33, v128
	v_add_f32_e32 v34, v34, v129
	v_add_f32_e32 v35, v35, v62
	v_add_f32_e32 v36, v36, v63
	v_add_f32_e32 v37, v37, v64
	v_add_f32_e32 v38, v38, v41
	v_add_f32_e32 v39, v39, v12
	v_add_f32_e32 v40, v40, v13
	v_fma_f32 v24, v24, s58, v224
	v_fma_f32 v25, v25, s14, v224
	v_fma_f32 v31, v31, s36, v224
	v_fma_f32 v32, v32, s36, v224
	v_fma_f32 v33, v33, s36, v224
	v_fma_f32 v34, v34, s36, v224
	v_fma_f32 v35, v35, s36, v224
	v_fma_f32 v36, v36, s36, v224
	v_fma_f32 v37, v37, s36, v224
	v_fma_f32 v38, v38, s36, v224
	v_fma_f32 v39, v39, s36, v224
	v_fma_f32 v40, v40, s36, v224
	v_rsq_f32_e32 v24, v24
	v_rsq_f32_e32 v25, v25
	v_rsq_f32_e32 v31, v31
	v_rsq_f32_e32 v32, v32
	v_rsq_f32_e32 v33, v33
	v_rsq_f32_e32 v34, v34
	v_rsq_f32_e32 v35, v35
	v_rsq_f32_e32 v36, v36
	v_rsq_f32_e32 v37, v37
	v_rsq_f32_e32 v38, v38
	v_rsq_f32_e32 v39, v39
	v_rsq_f32_e32 v40, v40
	v_mul_f32_e32 v114, v31, v114
	v_mul_f32_e32 v115, v32, v115
	v_mul_f32_e32 v116, v33, v116
	v_mul_f32_e32 v117, v34, v117
	v_mul_f32_e32 v118, v35, v118
	v_mul_f32_e32 v119, v36, v119
	v_mul_f32_e32 v120, v37, v120
	v_mul_f32_e32 v121, v38, v121
	v_mul_f32_e32 v122, v39, v122
	v_mul_f32_e32 v123, v40, v123
	v_mul_f32_e32 v114, v28, v114
	v_mul_f32_e32 v115, v28, v115
	v_mul_f32_e32 v116, v28, v116
	v_mul_f32_e32 v117, v28, v117
	v_mul_f32_e32 v118, v28, v118
	v_mul_f32_e32 v119, v28, v119
	v_mul_f32_e32 v120, v28, v120
	v_mul_f32_e32 v121, v28, v121
	v_mul_f32_e32 v122, v29, v122
	v_mul_f32_e32 v123, v29, v123
	ds_bpermute_b32 v124, v61, v114
	ds_bpermute_b32 v125, v61, v115
	ds_bpermute_b32 v126, v61, v116
	ds_bpermute_b32 v127, v61, v117
	ds_bpermute_b32 v128, v61, v118
	ds_bpermute_b32 v129, v61, v119
	ds_bpermute_b32 v62, v61, v120
	ds_bpermute_b32 v63, v61, v121
	ds_bpermute_b32 v64, v61, v122
	ds_bpermute_b32 v41, v61, v123
	v_mul_f32_e32 v14, v24, v14
	v_mul_f32_e32 v15, v24, v15
	v_mul_f32_e32 v16, v24, v16
	v_mul_f32_e32 v17, v24, v17
	v_mul_f32_e32 v18, v24, v18
	v_mul_f32_e32 v19, v24, v19
	v_mul_f32_e32 v20, v25, v20
	v_mul_f32_e32 v21, v25, v21
	v_mul_f32_e32 v22, v25, v22
	v_mul_f32_e32 v23, v25, v23
	v_fma_mixlo_f16 v88, v48, v14, 0
	v_fma_mixlo_f16 v89, v49, v15, 0
	v_fma_mixlo_f16 v90, v50, v16, 0
	v_fma_mixlo_f16 v91, v51, v17, 0
	v_fma_mixlo_f16 v92, v52, v18, 0
	v_fma_mixlo_f16 v93, v53, v19, 0
	v_fma_mixlo_f16 v94, v54, v20, 0
	v_fma_mixlo_f16 v95, v55, v21, 0
	v_fma_mixlo_f16 v96, v56, v22, 0
	v_fma_mixlo_f16 v97, v57, v23, 0
	global_store_short v58, v88, s[12:13]
	global_store_short v58, v89, s[12:13] offset:128
	global_store_short v58, v90, s[12:13] offset:256
	global_store_short v58, v91, s[12:13] offset:384
	global_store_short v58, v92, s[12:13] offset:512
	global_store_short v58, v93, s[12:13] offset:640
	global_store_short v58, v94, s[12:13] offset:768
	global_store_short v58, v95, s[12:13] offset:896
	global_store_short v58, v96, s[12:13] offset:1024
	global_store_short v58, v97, s[12:13] offset:1152
	s_waitcnt lgkmcnt(9)
	v_mul_f32_e32 v124, v103, v124
	s_waitcnt lgkmcnt(8)
	v_mul_f32_e32 v125, v103, v125
	s_waitcnt lgkmcnt(7)
	v_mul_f32_e32 v126, v103, v126
	s_waitcnt lgkmcnt(6)
	v_mul_f32_e32 v127, v103, v127
	s_waitcnt lgkmcnt(5)
	v_mul_f32_e32 v128, v103, v128
	s_waitcnt lgkmcnt(4)
	v_mul_f32_e32 v129, v103, v129
	s_waitcnt lgkmcnt(3)
	v_mul_f32_e32 v62, v103, v62
	s_waitcnt lgkmcnt(2)
	v_mul_f32_e32 v63, v103, v63
	s_waitcnt lgkmcnt(1)
	v_mul_f32_e32 v64, v103, v64
	s_waitcnt lgkmcnt(0)
	v_mul_f32_e32 v41, v103, v41
	v_cndmask_b32_e64 v124, v124, -v124, s[38:39]
	v_cndmask_b32_e64 v125, v125, -v125, s[38:39]
	v_cndmask_b32_e64 v126, v126, -v126, s[38:39]
	v_cndmask_b32_e64 v127, v127, -v127, s[38:39]
	v_cndmask_b32_e64 v128, v128, -v128, s[38:39]
	v_cndmask_b32_e64 v129, v129, -v129, s[38:39]
	v_cndmask_b32_e64 v62, v62, -v62, s[38:39]
	v_cndmask_b32_e64 v63, v63, -v63, s[38:39]
	v_cndmask_b32_e64 v64, v64, -v64, s[38:39]
	v_cndmask_b32_e64 v41, v41, -v41, s[38:39]
	v_fmac_f32_e32 v124, v102, v114
	v_fmac_f32_e32 v125, v102, v115
	v_fmac_f32_e32 v126, v102, v116
	v_fmac_f32_e32 v127, v102, v117
	v_fmac_f32_e32 v128, v102, v118
	v_fmac_f32_e32 v129, v102, v119
	v_fmac_f32_e32 v62, v102, v120
	v_fmac_f32_e32 v63, v102, v121
	v_fma_mixlo_f16 v104, v124, s59, 0
	v_fma_mixlo_f16 v105, v125, s59, 0
	v_fma_mixlo_f16 v106, v126, s59, 0
	v_fma_mixlo_f16 v107, v127, s59, 0
	v_fma_mixlo_f16 v108, v128, s59, 0
	v_fma_mixlo_f16 v109, v129, s59, 0
	v_fma_mixlo_f16 v110, v62, s59, 0
	v_fma_mixlo_f16 v111, v63, s59, 0
	v_fma_mixlo_f16 v112, v102, v122, v64
	v_fma_mixlo_f16 v113, v102, v123, v41
	global_store_short v80, v104, s[22:23]
	global_store_short v81, v105, s[22:23]
	global_store_short v82, v106, s[22:23]
	global_store_short v83, v107, s[22:23]
	global_store_short v84, v108, s[22:23]
	global_store_short v85, v109, s[22:23]
	global_store_short v86, v110, s[22:23]
	global_store_short v87, v111, s[22:23]
	global_store_short v80, v112, s[34:35]
	global_store_short v81, v113, s[34:35]
	s_and_b64 vcc, exec, s[42:43]
	s_cbranch_vccz .Lprep_kr_done
	v_cmp_gt_u32_e64 s[8:9], 16, v27
	s_nop 1
	s_and_saveexec_b64 s[8:9], s[8:9]
	v_cvt_f32_f16_e32 v124, v99
	v_mul_f32_e32 v125, v101, v124
	v_mul_f32_e32 v124, v100, v124
	v_fma_mixlo_f16 v125, v100, v98, -v125 op_sel_hi:[0,1,0]
	v_fma_mixlo_f16 v124, v101, v98, v124 op_sel_hi:[0,1,0]
	global_store_short v58, v125, s[16:17]
	global_store_short v58, v124, s[16:17] offset:32
	s_or_b64 exec, exec, s[8:9]
.Lprep_kr_done:
	s_cmp_lt_i32 s46, 0x8800
	s_cbranch_scc1 .Lprep_loop

; #define MFMA(a, b, c) __builtin_amdgcn_mfma_f32_32x32x16_f16((a), (b), (c), 0, 0, 0)
; DI void scan_chain_c(const P& p, int l, int chain, char* smem, const XcdBarrier* xb, const int* hint, int nhs) {
;     ...
;     {
;       f32x16 acc;
; #pragma unroll
;       for (int i = 0; i < 16; ++i) acc[i] = 0.f;
; #pragma unroll
;       for (int ks = 0; ks < 4; ++ks) acc = MFMA(__builtin_bit_cast(h16x8, af[ks]), bf[ks], acc);
;       float* rw = raw + mat * 2048 + nblk * 32 + r;
; #pragma unroll
;       for (int i = 0; i < 16; ++i) rw[(4 * hh + (i & 3) + 8 * (i >> 2)) * 64] = acc[i];
;     }
;     __syncthreads();
;     const int arrived = *sflag;
;     float lw[8], kkv[8], bbv[8], kmv[8], rrv[8], vvv[8], cl[8];
;     float run = 0.f;
;     const int cc = h * 64 + lane;
;     const float w0 = p.in[I_W0][(l * 2 + d) * 512 + cc], a0 = p.in[I_A0][(l * 2 + d) * 512 + cc];
;     const float kkc = p.in[I_KK][l * 512 + cc], kac = p.in[I_KA][l * 512 + cc], rkc = p.in[I_RK][l * 512 + cc];
;     const float trA = cvp[(d ? 3072 : 0) + cc], tr1 = cvp[1536 + cc], trC = cvp[(d ? 0 : 3072) + cc];
;     const float tkA = cvp[(d ? 3072 : 0) + 512 + cc], tk1 = cvp[1536 + 512 + cc], tkC = cvp[(d ? 0 : 3072) + 512 + cc];
;     const float tvA = cvp[(d ? 3072 : 0) + 1024 + cc], tv1 = cvp[1536 + 1024 + cc], tvC = cvp[(d ? 0 : 3072) + 1024 + cc];
.LBB0_2335:
	s_or_b64 exec, exec, s[0:1]
	s_waitcnt vmcnt(3)
	v_mfma_f32_32x32x16_f16 v[18:33], v[50:53], v[34:37], 0
	v_ashrrev_i32_e32 v150, 5, v80
	v_and_b32_e32 v148, 31, v80
	v_lshlrev_b32_e32 v77, 2, v150
	v_lshl_add_u32 v0, v148, 2, v112
	v_lshlrev_b32_e32 v164, 10, v150
	v_or_b32_e32 v179, 1, v77
	v_or_b32_e32 v178, 2, v77
	s_waitcnt vmcnt(2)
	v_mfma_f32_32x32x16_f16 v[18:33], v[54:57], v[38:41], v[18:33]
	v_or_b32_e32 v177, 3, v77
	v_add_u32_e32 v176, 8, v77
	v_add_u32_e32 v175, 9, v77
	v_add_u32_e32 v174, 10, v77
	v_add_u32_e32 v76, v0, v164
	v_lshlrev_b32_e32 v163, 8, v179
	v_lshlrev_b32_e32 v162, 8, v178
	s_waitcnt vmcnt(1)
	v_mfma_f32_32x32x16_f16 v[18:33], v[58:61], v[42:45], v[18:33]
	v_lshlrev_b32_e32 v161, 8, v177
	v_lshlrev_b32_e32 v160, 8, v176
	v_lshlrev_b32_e32 v159, 8, v175
	v_lshlrev_b32_e32 v157, 8, v174
	v_add_u32_e32 v173, 11, v77
	v_add_u32_e32 v78, v0, v163
	v_add_u32_e32 v81, v0, v162
	s_waitcnt vmcnt(0)
	v_mfma_f32_32x32x16_f16 v[18:33], v[62:65], v[46:49], v[18:33]
	v_add_u32_e32 v82, v0, v161
	v_add_u32_e32 v83, v0, v160
	v_add_u32_e32 v149, v0, v159
	v_lshlrev_b32_e32 v158, 8, v173
	v_add_u32_e32 v172, 16, v77
	v_lshlrev_b32_e32 v156, 8, v172
	v_add_u32_e32 v171, 17, v77
	s_nop 4
	ds_write_b32 v76, v18
	ds_write_b32 v78, v19
	ds_write_b32 v81, v20
	ds_write_b32 v82, v21
	ds_write_b32 v83, v22
	ds_write_b32 v149, v23
	v_add_u32_e32 v18, v0, v157
	ds_write_b32 v18, v24
	v_add_u32_e32 v18, v0, v158
	ds_write_b32 v18, v25
	v_add_u32_e32 v18, v0, v156
	v_lshlrev_b32_e32 v155, 8, v171
	v_add_u32_e32 v170, 18, v77
	ds_write_b32 v18, v26
	v_add_u32_e32 v18, v0, v155
	v_lshlrev_b32_e32 v154, 8, v170
	v_add_u32_e32 v169, 19, v77
	ds_write_b32 v18, v27
	v_add_u32_e32 v18, v0, v154
	v_lshlrev_b32_e32 v153, 8, v169
	v_add_u32_e32 v168, 24, v77
	ds_write_b32 v18, v28
	v_add_u32_e32 v18, v0, v153
	v_lshlrev_b32_e32 v81, 8, v168
	v_add_u32_e32 v167, 25, v77
	ds_write_b32 v18, v29
	v_add_u32_e32 v18, v0, v81
	v_lshlrev_b32_e32 v82, 8, v167
	v_add_u32_e32 v166, 26, v77
	ds_write_b32 v18, v30
	v_add_u32_e32 v18, v0, v82
	v_lshlrev_b32_e32 v83, 8, v166
	ds_write_b32 v18, v31
	v_add_u32_e32 v18, v0, v83
	ds_write_b32 v18, v32
	v_add_u32_e32 v18, s33, v80
	v_add_u32_e32 v20, s78, v18
	v_add_u32_e32 v165, 27, v77
	v_ashrrev_i32_e32 v21, 31, v20
	v_readlane_b32 s52, v252, 33
	v_lshlrev_b32_e32 v152, 8, v165
	v_lshlrev_b64 v[20:21], 2, v[20:21]
	v_readlane_b32 s60, v252, 41
	v_readlane_b32 s61, v252, 42
	v_add_u32_e32 v0, v0, v152
	ds_write_b32 v0, v33
	v_lshl_add_u64 v[22:23], s[60:61], 0, v[20:21]
	s_waitcnt lgkmcnt(0)
	s_barrier
	s_waitcnt vmcnt(0)
	s_movk_i32 s0, 0x1000
	s_mov_b32 s11, s37
	s_mov_b64 s[26:27], s[90:91]
	s_mov_b64 s[18:19], s[94:95]
	s_mov_b64 s[16:17], s[92:93]
	v_readlane_b32 s66, v252, 47
	v_readlane_b32 s67, v252, 48
	v_readlane_b32 s80, v253, 4
	v_readlane_b32 s81, v253, 5
	v_readlane_b32 s82, v253, 6
	v_readlane_b32 s83, v253, 7
	v_readlane_b32 s56, v252, 37
	v_readlane_b32 s57, v252, 38
	s_cmp_lg_u32 s25, 0
	s_cbranch_scc1 .Lscan_consts_ready
	global_load_dword v220, v[22:23], off
	v_add_u32_e32 v24, s71, v18
	v_ashrrev_i32_e32 v19, 31, v18
	v_ashrrev_i32_e32 v25, 31, v24
	v_lshl_add_u64 v[30:31], v[18:19], 2, s[4:5]
	v_lshl_add_u64 v[28:29], v[24:25], 2, s[4:5]
	v_add_co_u32_e32 v32, vcc, s0, v30
	s_nop 1
	v_addc_co_u32_e32 v33, vcc, 0, v31, vcc
	v_lshl_add_u64 v[180:181], v[30:31], 0, s[10:11]
	global_load_dword v221, v[28:29], off
	global_load_dword v222, v[32:33], off offset:2048
	global_load_dword v223, v[180:181], off
	v_add_u32_e32 v28, s2, v18
	v_add_u32_e32 v22, s3, v18
	v_ashrrev_i32_e32 v29, 31, v28
	v_add_u32_e32 v24, 0x400, v24
	v_lshl_add_u64 v[32:33], v[28:29], 2, s[4:5]
	v_add_co_u32_e32 v28, vcc, s15, v30
	v_add_u32_e32 v30, s77, v18
	v_ashrrev_i32_e32 v25, 31, v24
	v_ashrrev_i32_e32 v23, 31, v22
	v_addc_co_u32_e32 v29, vcc, 0, v31, vcc
	v_ashrrev_i32_e32 v31, 31, v30
	v_lshl_add_u64 v[24:25], v[24:25], 2, s[4:5]
	v_lshlrev_b64 v[22:23], 2, v[22:23]
	v_lshl_add_u64 v[30:31], v[30:31], 2, s[4:5]
	global_load_dword v228, v[28:29], off
	global_load_dword v229, v[30:31], off
	global_load_dword v230, v[24:25], off
	global_load_dword v231, v[28:29], off offset:2048
	global_load_dword v232, v[32:33], off
	v_lshl_add_u64 v[24:25], s[66:67], 0, v[22:23]
	global_load_dword v233, v[24:25], off
	v_lshl_add_u64 v[24:25], s[80:81], 0, v[22:23]
	global_load_dword v234, v[24:25], off
	v_add_u32_e32 v18, s24, v18
	v_lshl_add_u64 v[22:23], s[82:83], 0, v[22:23]
	global_load_dword v235, v[22:23], off
	v_ashrrev_i32_e32 v19, 31, v18
	v_lshl_add_u64 v[18:19], v[18:19], 2, s[4:5]
	v_lshl_add_u64 v[20:21], s[56:57], 0, v[20:21]
	global_load_dword v236, v[20:21], off
	global_load_dword v237, v[18:19], off
	s_waitcnt vmcnt(0)

; DI float sigmoidf_(float x) { return __builtin_amdgcn_rcpf(1.f + __expf(-x)); }
; DI void scan_chain_c(const P& p, int l, int chain, char* smem, const XcdBarrier* xb, const int* hint, int nhs) {
;     ...
;       const float rr = trA * (float)xr[e] + tr1 * (float)xr[e + 1] + trC * (float)xr[e + 2];
;       const float kx = tkA * (float)xk[e] + tk1 * (float)xk[e + 1] + tkC * (float)xk[e + 2];
;       const float vv = tvA * (float)xv[e] + tv1 * (float)xv[e + 1] + tvC * (float)xv[e + 2];
;       const float wr = w0 + raw[tt * 64 + lane], ar = a0 + raw[2048 + tt * 64 + lane];
;       const float z = -wr;
;       const float sp = fmaxf(z, 0.f) + __logf(1.f + __expf(-fabsf(z)));
;       const float lgw = -__expf(-sp - 0.5f);
;       const float aa = sigmoidf_(ar);
;       const float kkr = kx * kkc;
;       const float kkn = kkr * __builtin_amdgcn_rsqf(fmaxf(wave_sum(kkr * kkr), 1e-24f));
;       const float km = kx * (1.f + (aa - 1.f) * kac);
;       const float bon = wave_sum(rr * km * rkc);
;       if (lane == 0) bs[((size_t)d * TA + row) * 8 + h] = bon;
;       run += lgw;
;       lw[e] = lgw; cl[e] = run; kkv[e] = kkn; bbv[e] = kkn * aa; kmv[e] = km; rrv[e] = rr; vvv[e] = vv;
;     }
;     tot[w * 64 + lane] = run;
;     __syncthreads();
;     {
;       const float t0 = tot[lane], t1 = tot[64 + lane], t2 = tot[128 + lane], t3 = tot[192 + lane];
;       const float total = t0 + t1 + t2 + t3;
;       const float prefix = (w > 0 ? t0 : 0.f) + (w > 1 ? t1 : 0.f) + (w > 2 ? t2 : 0.f);
;       if (w == 0) GL[lane] = __expf(total);
;       b16x8 bgv, kgv, vtv;
; #pragma unroll
;       for (int e = 0; e < 8; ++e) {
;         const int tt = 8 * w + e;
;         const float g = prefix + cl[e];
;         const float eg = __expf(g), ege = __expf(g - lw[e]);
;         const float eng = __builtin_amdgcn_rcpf(eg);
;         const float egl = __expf(total - g);
;         Qt[tt * 72 + lane] = (b16)(kkv[e] * ege);
;         Rt[tt * 72 + lane] = (b16)(rrv[e] * eg);
;         Bt[tt * 72 + lane] = (b16)(bbv[e] * eng);
;         Kt[tt * 72 + lane] = (b16)(kmv[e] * eng);
;         bgv[e] = (b16)(bbv[e] * egl);
;         kgv[e] = (b16)(kmv[e] * egl);
;         vtv[e] = (b16)vvv[e];
.LBB0_2353:
	s_or_b64 exec, exec, s[0:1]
	v_add_f32_e32 v25, v213, v214
	v_max_f32_e32 v25, 0x179abe15, v25
	v_rsq_f32_e32 v25, v25
	v_cndmask_b32_e64 v26, 0, v26, s[42:43]
	v_cndmask_b32_e64 v27, 0, v27, s[44:45]
	v_cndmask_b32_e64 v24, 0, v24, s[46:47]
	v_mul_f32_e32 v206, v206, v25
	v_add_f32_e32 v25, v26, v27
	v_add_f32_e32 v26, v244, v245
	v_max_f32_e32 v26, 0x179abe15, v26
	v_rsq_f32_e32 v26, v26
	v_cvt_f32_f16_e32 v27, v111
	v_add_f32_e32 v213, v25, v24
	v_cvt_f32_f16_e32 v24, v123
	v_mul_f32_e32 v214, v242, v26
	v_add_f32_e32 v26, v238, v239
	v_max_f32_e32 v26, 0x179abe15, v26
	v_rsq_f32_e32 v26, v26
	v_cvt_f32_f16_e32 v217, v108
	v_mul_f32_e32 v24, v28, v24
	v_fma_mix_f32 v24, v0, v111, v24 op_sel_hi:[0,1,0]
	v_mul_f32_e32 v212, v212, v26
	v_mul_f32_e32 v26, v28, v27
	v_add_f32_e32 v27, v204, v205
	v_max_f32_e32 v27, 0x179abe15, v27
	v_rsq_f32_e32 v27, v27
	v_fma_mix_f32 v26, v0, v108, v26 op_sel_hi:[0,1,0]
	s_waitcnt vmcnt(0)
	v_fma_mix_f32 v204, v29, v123, v26 op_sel_hi:[0,1,0]
	v_cvt_f32_f16_e32 v26, v104
	v_mul_f32_e32 v205, v199, v27
	v_mul_f32_e32 v27, v28, v217
	v_fma_mix_f32 v27, v0, v104, v27 op_sel_hi:[0,1,0]
	v_add_f32_e32 v183, v183, v184
	v_fma_mix_f32 v216, v29, v147, v24 op_sel_hi:[0,1,0]
	v_mul_f32_e32 v24, v211, v212
	v_add_f32_e32 v195, v195, v196
	v_fma_mix_f32 v196, v29, v111, v27 op_sel_hi:[0,1,0]
	v_cvt_f32_f16_e32 v211, v102
	v_add_f32_e32 v27, v189, v190
	v_max_f32_e32 v183, 0x179abe15, v183
	v_max_f32_e32 v27, 0x179abe15, v27
	v_rsq_f32_e32 v183, v183
	v_mul_f32_e32 v26, v28, v26
	v_rsq_f32_e32 v27, v27
	v_cvt_f32_f16_e32 v190, v98
	v_fma_mix_f32 v26, v0, v102, v26 op_sel_hi:[0,1,0]
	v_fma_mix_f32 v189, v29, v108, v26 op_sel_hi:[0,1,0]
	v_mul_f32_e32 v26, v28, v211
	v_fma_mix_f32 v26, v0, v98, v26 op_sel_hi:[0,1,0]
	v_mul_f32_e32 v182, v182, v183
	v_add_f32_e32 v78, v78, v151
	v_mul_f32_e32 v188, v188, v27
	v_fma_mix_f32 v184, v29, v104, v26 op_sel_hi:[0,1,0]
	v_mul_f32_e32 v26, v181, v182
	v_mul_f32_e32 v181, v28, v190
	v_max_f32_e32 v78, 0x179abe15, v78
	v_mul_f32_e32 v27, v186, v188
	v_cvt_f32_f16_e32 v186, v96
	v_rsq_f32_e32 v78, v78
	v_fma_mix_f32 v151, v0, v96, v181 op_sel_hi:[0,1,0]
	v_cvt_f32_f16_e32 v181, v92
	v_sub_f32_e32 v202, 0, v215
	v_mul_f32_e32 v33, v33, v78
	v_mul_f32_e32 v78, v28, v186
	v_mul_f32_e32 v28, v28, v181
	v_fma_mix_f32 v78, v0, v92, v78 op_sel_hi:[0,1,0]
	v_fma_mix_f32 v0, v0, v90, v28 op_sel_hi:[0,1,0]
	v_add_f32_e32 v28, v202, v213
	v_fma_mix_f32 v151, v29, v102, v151 op_sel_hi:[0,1,0]
	v_fma_mix_f32 v78, v29, v98, v78 op_sel_hi:[0,1,0]
	v_fma_mix_f32 v0, v29, v96, v0 op_sel_hi:[0,1,0]
	v_mul_f32_e32 v29, 0x3fb8aa3b, v28
	v_exp_f32_e32 v29, v29
	v_add_f32_e32 v181, v215, v28
	v_mul_f32_e32 v181, 0x3fb8aa3b, v181
	v_exp_f32_e32 v181, v181
	v_rcp_f32_e32 v183, v29
	v_sub_f32_e32 v28, v247, v28
	v_mul_f32_e32 v29, v30, v29
	v_mul_f32_e32 v32, v32, v33
	v_mul_f32_e32 v28, 0x3fb8aa3b, v28
	v_mul_f32_e32 v33, v33, v181
	v_add_lshl_u32 v181, v80, v144, 1
	v_cvt_pk_bf16_f32 v29, v29, s0
	v_exp_f32_e32 v28, v28
	ds_write_b16 v181, v29 offset:22016
	v_mul_f32_e32 v29, v32, v183
	v_cvt_pk_bf16_f32 v29, v29, s0
	ds_write_b16 v181, v29 offset:26624
	v_mul_f32_e32 v29, v31, v183
	v_cvt_pk_bf16_f32 v29, v29, s0
	ds_write_b16 v181, v29 offset:31232
	v_mul_f32_e32 v29, v32, v28
	v_mul_f32_e32 v28, v31, v28
	v_cvt_pk_bf16_f32 v31, v28, s0
	v_add_f32_e32 v28, v210, v213
	v_cvt_pk_bf16_f32 v30, v29, s0
	v_mul_f32_e32 v29, 0x3fb8aa3b, v28
	v_exp_f32_e32 v29, v29
	v_cvt_pk_bf16_f32 v33, v33, s0
	ds_write_b16 v181, v33 offset:17408
	v_add_f32_e32 v32, v200, v28
	v_rcp_f32_e32 v33, v29
	v_mul_f32_e32 v32, 0x3fb8aa3b, v32
	v_mul_f32_e32 v29, v76, v29
	v_exp_f32_e32 v32, v32
	v_cvt_pk_bf16_f32 v29, v29, s0
	ds_write_b16 v181, v29 offset:22160
	v_mul_f32_e32 v29, v26, v33
	v_cvt_pk_bf16_f32 v29, v29, s0
	ds_write_b16 v181, v29 offset:26768
	v_mul_f32_e32 v29, v18, v33
	v_mul_f32_e32 v32, v182, v32
	v_cvt_pk_bf16_f32 v29, v29, s0
	v_cvt_pk_bf16_f32 v32, v32, s0
	ds_write_b16 v181, v29 offset:31376
	v_add_f32_e32 v29, v219, v213
	ds_write_b16 v181, v32 offset:17552
	v_mul_f32_e32 v32, 0x3fb8aa3b, v29
	v_exp_f32_e32 v32, v32
	v_sub_f32_e32 v28, v247, v28
	v_add_f32_e32 v33, v248, v29
	v_sub_f32_e32 v29, v247, v29
	v_rcp_f32_e32 v76, v32
	v_mul_f32_e32 v28, 0x3fb8aa3b, v28
	v_mul_f32_e32 v29, 0x3fb8aa3b, v29
	v_exp_f32_e32 v28, v28
	v_exp_f32_e32 v29, v29
	v_mul_f32_e32 v32, v180, v32
	v_cvt_pk_bf16_f32 v32, v32, s0
	ds_write_b16 v181, v32 offset:22304
	v_mul_f32_e32 v32, v27, v76
	v_mul_f32_e32 v33, 0x3fb8aa3b, v33
	v_cvt_pk_bf16_f32 v32, v32, s0
	v_exp_f32_e32 v33, v33
	ds_write_b16 v181, v32 offset:26912
	v_mul_f32_e32 v32, v19, v76
	v_pk_mul_f32 v[26:27], v[26:27], v[28:29]
	v_pk_mul_f32 v[18:19], v[18:19], v[28:29]
	v_add_f32_e32 v28, v240, v213
	v_mul_f32_e32 v29, 0x3fb8aa3b, v28
	v_exp_f32_e32 v29, v29
	v_max_f32_e32 v195, 0x179abe15, v195
	v_rsq_f32_e32 v195, v195
	v_mul_f32_e32 v33, v188, v33
	v_cvt_pk_bf16_f32 v33, v33, s0
	v_cvt_pk_bf16_f32 v32, v32, s0
	s_mov_b32 s0, 0x5040100
	v_cvt_pk_bf16_f32 v19, v18, v19
	v_cvt_pk_bf16_f32 v27, v26, v27
	v_perm_b32 v18, v19, v31, s0
	v_rcp_f32_e32 v31, v29
	v_perm_b32 v26, v27, v30, s0
	v_add_f32_e32 v30, v209, v28
	v_mul_f32_e32 v193, v193, v195
	v_mul_f32_e32 v30, 0x3fb8aa3b, v30
	v_mul_f32_e32 v29, v185, v29
	v_mul_f32_e32 v199, v198, v205
	v_mul_f32_e32 v198, v192, v193
	v_exp_f32_e32 v30, v30
	v_cvt_pk_bf16_f32 v29, v29, s0
	ds_write_b16 v181, v29 offset:22448
	v_mul_f32_e32 v29, v198, v31
	v_cvt_pk_bf16_f32 v29, v29, s0
	ds_write_b16 v181, v29 offset:27056
	v_mul_f32_e32 v29, v20, v31
	v_mul_f32_e32 v30, v193, v30
	v_cvt_pk_bf16_f32 v29, v29, s0
; DI void scan_chain_c(const P& p, int l, int chain, char* smem, const XcdBarrier* xb, const int* hint, int nhs) {
;     ...
;       b16x8 bgv, kgv, vtv;
; #pragma unroll
;       for (int e = 0; e < 8; ++e) {
;         const int tt = 8 * w + e;
;         const float g = prefix + cl[e];
;         const float eg = __expf(g), ege = __expf(g - lw[e]);
;         const float eng = __builtin_amdgcn_rcpf(eg);
;         const float egl = __expf(total - g);
;         Qt[tt * 72 + lane] = (b16)(kkv[e] * ege);
;         Rt[tt * 72 + lane] = (b16)(rrv[e] * eg);
;         Bt[tt * 72 + lane] = (b16)(bbv[e] * eng);
;         Kt[tt * 72 + lane] = (b16)(kmv[e] * eng);
;         bgv[e] = (b16)(bbv[e] * egl);
;         kgv[e] = (b16)(kmv[e] * egl);
;         vtv[e] = (b16)vvv[e];
;       }
;       *(b16x8*)(BgT + lane * 40 + 8 * w) = bgv;
;       *(b16x8*)(KgT + lane * 40 + 8 * w) = kgv;
;       *(b16x8*)(VT + lane * 40 + 8 * w) = vtv;
;     }
;     __syncthreads();
	v_cvt_pk_bf16_f32 v30, v30, s0
	ds_write_b16 v181, v29 offset:31664
	v_add_f32_e32 v29, v227, v213
	ds_write_b16 v181, v30 offset:17840
	v_mul_f32_e32 v30, 0x3fb8aa3b, v29
	v_exp_f32_e32 v30, v30
	ds_write_b16 v181, v32 offset:31520
	v_add_f32_e32 v31, v249, v29
	v_sub_f32_e32 v28, v247, v28
	v_rcp_f32_e32 v32, v30
	v_mul_f32_e32 v31, 0x3fb8aa3b, v31
	v_sub_f32_e32 v29, v247, v29
	v_mul_f32_e32 v28, 0x3fb8aa3b, v28
	v_exp_f32_e32 v31, v31
	v_mul_f32_e32 v29, 0x3fb8aa3b, v29
	v_mul_f32_e32 v30, v187, v30
	v_exp_f32_e32 v28, v28
	v_exp_f32_e32 v29, v29
	v_cvt_pk_bf16_f32 v30, v30, s0
	ds_write_b16 v181, v30 offset:22592
	v_mul_f32_e32 v30, v199, v32
	v_cvt_pk_bf16_f32 v30, v30, s0
	v_mul_f32_e32 v31, v205, v31
	ds_write_b16 v181, v30 offset:27200
	v_mul_f32_e32 v30, v21, v32
	v_cvt_pk_bf16_f32 v31, v31, s0
	v_cvt_pk_bf16_f32 v30, v30, s0
	v_pk_mul_f32 v[20:21], v[20:21], v[28:29]
	ds_write_b16 v181, v31 offset:17984
	ds_write_b16 v181, v30 offset:31808
	v_pk_mul_f32 v[30:31], v[198:199], v[28:29]
	v_cvt_pk_bf16_f32 v29, v20, v21
	v_add_f32_e32 v20, v226, v213
	v_mul_f32_e32 v21, 0x3fb8aa3b, v20
	v_exp_f32_e32 v21, v21
	v_cvt_pk_bf16_f32 v30, v30, v31
	v_add_f32_e32 v28, v243, v20
	v_mul_f32_e32 v28, 0x3fb8aa3b, v28
	v_rcp_f32_e32 v31, v21
	v_mul_f32_e32 v21, v191, v21
	v_exp_f32_e32 v28, v28
	v_cvt_pk_bf16_f32 v21, v21, s0
	ds_write_b16 v181, v21 offset:22736
	v_mul_f32_e32 v21, v24, v31
	v_cvt_pk_bf16_f32 v21, v21, s0
	ds_write_b16 v181, v21 offset:27344
	v_mul_f32_e32 v21, v22, v31
	v_mul_f32_e32 v28, v212, v28
	v_cvt_pk_bf16_f32 v21, v21, s0
	v_cvt_pk_bf16_f32 v28, v28, s0
	ds_write_b16 v181, v21 offset:31952
	v_add_f32_e32 v21, v251, v213
	ds_write_b16 v181, v28 offset:18128
	v_mul_f32_e32 v28, 0x3fb8aa3b, v21
	v_exp_f32_e32 v28, v28
	v_sub_f32_e32 v20, v247, v20
	v_add_f32_e32 v31, v250, v21
	v_sub_f32_e32 v21, v247, v21
	v_mul_f32_e32 v20, 0x3fb8aa3b, v20
	v_rcp_f32_e32 v32, v28
	v_mul_f32_e32 v21, 0x3fb8aa3b, v21
	v_exp_f32_e32 v20, v20
	v_exp_f32_e32 v21, v21
	v_mul_f32_e32 v28, v194, v28
	v_mul_f32_e32 v25, v241, v214
	v_cvt_pk_bf16_f32 v28, v28, s0
	ds_write_b16 v181, v28 offset:22880
	v_mul_f32_e32 v28, v25, v32
	v_cvt_pk_bf16_f32 v28, v28, s0
	v_pk_mul_f32 v[24:25], v[24:25], v[20:21]
	v_pk_mul_f32 v[20:21], v[22:23], v[20:21]
	v_add_f32_e32 v22, v246, v213
	ds_write_b16 v181, v28 offset:27488
	v_mul_f32_e32 v28, v23, v32
	v_mul_f32_e32 v23, 0x3fb8aa3b, v22
	v_exp_f32_e32 v23, v23
	v_cvt_pk_bf16_f32 v21, v20, v21
	v_alignbit_b32 v19, v29, v19, 16
	v_alignbit_b32 v20, v21, v29, 16
	v_rcp_f32_e32 v29, v23
	v_cvt_pk_bf16_f32 v24, v24, v25
	v_add_f32_e32 v25, v208, v22
	v_sub_f32_e32 v22, v247, v22
	v_mul_f32_e32 v23, v197, v23
	v_mul_f32_e32 v207, v207, v206
	v_mul_f32_e32 v31, 0x3fb8aa3b, v31
	v_mul_f32_e32 v22, 0x3fb8aa3b, v22
	v_cvt_pk_bf16_f32 v23, v23, s0
	v_exp_f32_e32 v31, v31
	v_mul_f32_e32 v25, 0x3fb8aa3b, v25
	v_exp_f32_e32 v22, v22
	ds_write_b16 v181, v23 offset:23024
	v_mul_f32_e32 v23, v207, v29
	v_exp_f32_e32 v25, v25
	v_cvt_pk_bf16_f32 v23, v23, s0
	ds_write_b16 v181, v23 offset:27632
	v_mul_f32_e32 v23, v201, v29
	v_cvt_pk_bf16_f32 v23, v23, s0
	v_mul_f32_e32 v31, v214, v31
	ds_write_b16 v181, v23 offset:32240
	v_mul_f32_e32 v23, v207, v22
	v_mul_f32_e32 v22, v201, v22
	v_cvt_pk_bf16_f32 v31, v31, s0
	v_cvt_pk_bf16_f32 v28, v28, s0
	v_mul_f32_e32 v25, v206, v25
	v_cvt_pk_bf16_f32 v23, v23, s0
	v_cvt_pk_bf16_f32 v22, v22, s0
	v_alignbit_b32 v27, v30, v27, 16
	ds_write_b16 v181, v31 offset:18272
	ds_write_b16 v181, v28 offset:32096
	v_alignbit_b32 v28, v24, v30, 16
	v_cvt_pk_bf16_f32 v25, v25, s0
	v_alignbit_b32 v29, v23, v24, 16
	v_alignbit_b32 v21, v22, v21, 16
	v_cvt_pk_bf16_f32 v22, v0, v78
	v_mad_u64_u32 v[30:31], s[0:1], v80, s76, v[66:67]
	v_mul_u32_u24_e32 v0, 0x48, v148
	ds_write_b16 v181, v33 offset:17696
	ds_write_b16 v181, v25 offset:18416
	v_cvt_pk_bf16_f32 v25, v204, v216
	v_cvt_pk_bf16_f32 v24, v189, v196
	v_cvt_pk_bf16_f32 v23, v151, v184
	ds_write_b128 v30, v[26:29] offset:35840
	ds_write_b128 v30, v[18:21] offset:40960
	ds_write_b128 v30, v[22:25] offset:46080
	v_lshlrev_b32_e32 v0, 1, v0
	v_lshlrev_b32_e32 v22, 4, v150
	v_add3_u32 v76, v114, v0, v22
	s_waitcnt lgkmcnt(0)
	s_barrier
; #define MFMAB(a, b, c) __builtin_amdgcn_mfma_f32_32x32x16_bf16((a), (b), (c), 0, 0, 0)
; DI void scan_chain_c(const P& p, int l, int chain, char* smem, const XcdBarrier* xb, const int* hint, int nhs) {
;     ...
;     {
;       const b16* X = (w < 2) ? Qt : Rt;
;       const b16* Y = (w & 1) ? Kt : Bt;
;       f32x16 acc;
; #pragma unroll
;       for (int i = 0; i < 16; ++i) acc[i] = 0.f;
; #pragma unroll
;       for (int ks = 0; ks < 4; ++ks) {
;         b16x8 a = *(const b16x8*)(X + r * 72 + ks * 16 + 8 * hh);
;         b16x8 bb = *(const b16x8*)(Y + r * 72 + ks * 16 + 8 * hh);
;         acc = MFMAB(a, bb, acc);
;       }
; #pragma unroll
;       for (int i = 0; i < 16; ++i) {
;         const int t = 4 * hh + (i & 3) + 8 * (i >> 2);
;         const bool keep = (w < 2) ? (r < t) : (r <= t);
;         const float v = keep ? acc[i] : 0.f;
;         if (w == 0) Am[t * 36 + r] = v;
;         else if (w == 1) Bm[t * 40 + r] = (b16)v;
;         else if (w == 2) A2[t * 40 + r] = (b16)v;
;         else B2[t * 40 + r] = (b16)v;
;       }
	v_add3_u32 v0, v115, v0, v22
	ds_read_b128 v[180:183], v76
	ds_read_b128 v[184:187], v0
	ds_read_b128 v[188:191], v76 offset:32
	ds_read_b128 v[192:195], v0 offset:32
	ds_read_b128 v[196:199], v76 offset:64
	ds_read_b128 v[204:207], v0 offset:64
	ds_read_b128 v[208:211], v76 offset:96
	ds_read_b128 v[212:215], v0 offset:96
	v_lshlrev_b32_e32 v151, 3, v150
	v_lshlrev_b32_e32 v76, 1, v148
	s_waitcnt lgkmcnt(6)
	v_mfma_f32_32x32x16_bf16 v[18:33], v[180:183], v[184:187], 0
	s_waitcnt lgkmcnt(4)
	v_mfma_f32_32x32x16_bf16 v[18:33], v[188:191], v[192:195], v[18:33]
	s_waitcnt lgkmcnt(2)
	v_mfma_f32_32x32x16_bf16 v[18:33], v[196:199], v[204:207], v[18:33]
	s_waitcnt lgkmcnt(0)
	v_mfma_f32_32x32x16_bf16 v[18:33], v[208:211], v[212:215], v[18:33]
	v_sub_u32_e32 v180, v148, v77
	v_cndmask_b32_e64 v181, 1, 0, s[50:51]
	v_readfirstlane_b32 s0, v67
	v_sub_u32_e32 v180, v180, v181
	v_mul_u32_u24_e32 v182, 0x140, v150
	v_mul_u32_u24_e32 v183, 0x90, v148
	s_mul_i32 s1, s0, 0xa00
	s_add_i32 s1, s1, 0xf400
	v_lshl_add_u32 v182, v148, 1, v182
	v_lshl_add_u32 v183, v150, 4, v183
	v_add_u32_e32 v182, s1, v182
	s_cmp_eq_u32 s0, 0
	s_cbranch_scc1 .Lscan_s3_w0
	v_cmp_gt_i32_e64 vcc, 0, v180
	v_cmp_gt_i32_e64 s[0:1], 1, v180
	v_cmp_gt_i32_e64 s[12:13], 2, v180
	v_cmp_gt_i32_e64 s[14:15], 3, v180
	v_cndmask_b32_e32 v184, 0, v18, vcc
	v_cndmask_b32_e64 v185, 0, v19, s[0:1]
	v_cndmask_b32_e64 v186, 0, v20, s[12:13]
	v_cndmask_b32_e64 v187, 0, v21, s[14:15]
	v_cvt_pk_bf16_f32 v184, v184, v184
	v_cvt_pk_bf16_f32 v185, v185, v185
	v_cvt_pk_bf16_f32 v186, v186, v186
	v_cvt_pk_bf16_f32 v187, v187, v187
	ds_write_b16 v182, v184 offset:0
	ds_write_b16 v182, v185 offset:80
	ds_write_b16 v182, v186 offset:160
	ds_write_b16 v182, v187 offset:240
	v_cmp_gt_i32_e64 vcc, 8, v180
	v_cmp_gt_i32_e64 s[0:1], 9, v180
	v_cmp_gt_i32_e64 s[12:13], 10, v180
	v_cmp_gt_i32_e64 s[14:15], 11, v180
	v_cndmask_b32_e32 v188, 0, v22, vcc
	v_cndmask_b32_e64 v189, 0, v23, s[0:1]
	v_cndmask_b32_e64 v190, 0, v24, s[12:13]
	v_cndmask_b32_e64 v191, 0, v25, s[14:15]
	v_cvt_pk_bf16_f32 v188, v188, v188
	v_cvt_pk_bf16_f32 v189, v189, v189
	v_cvt_pk_bf16_f32 v190, v190, v190
	v_cvt_pk_bf16_f32 v191, v191, v191
	ds_write_b16 v182, v188 offset:640
	ds_write_b16 v182, v189 offset:720
	ds_write_b16 v182, v190 offset:800
	ds_write_b16 v182, v191 offset:880
	v_cmp_gt_i32_e64 vcc, 16, v180
	v_cmp_gt_i32_e64 s[0:1], 17, v180
	v_cmp_gt_i32_e64 s[12:13], 18, v180
	v_cmp_gt_i32_e64 s[14:15], 19, v180
	v_cndmask_b32_e32 v184, 0, v26, vcc
	v_cndmask_b32_e64 v185, 0, v27, s[0:1]
	v_cndmask_b32_e64 v186, 0, v28, s[12:13]
	v_cndmask_b32_e64 v187, 0, v29, s[14:15]
	v_cvt_pk_bf16_f32 v184, v184, v184
	v_cvt_pk_bf16_f32 v185, v185, v185
	v_cvt_pk_bf16_f32 v186, v186, v186
	v_cvt_pk_bf16_f32 v187, v187, v187
	ds_write_b16 v182, v184 offset:1280
	ds_write_b16 v182, v185 offset:1360
	ds_write_b16 v182, v186 offset:1440
	ds_write_b16 v182, v187 offset:1520
	v_cmp_gt_i32_e64 vcc, 24, v180
	v_cmp_gt_i32_e64 s[0:1], 25, v180
	v_cmp_gt_i32_e64 s[12:13], 26, v180
	v_cmp_gt_i32_e64 s[14:15], 27, v180
	v_cndmask_b32_e32 v188, 0, v30, vcc
	v_cndmask_b32_e64 v189, 0, v31, s[0:1]
	v_cndmask_b32_e64 v190, 0, v32, s[12:13]
	v_cndmask_b32_e64 v191, 0, v33, s[14:15]
	v_cvt_pk_bf16_f32 v188, v188, v188
	v_cvt_pk_bf16_f32 v189, v189, v189
	v_cvt_pk_bf16_f32 v190, v190, v190
	v_cvt_pk_bf16_f32 v191, v191, v191
	ds_write_b16 v182, v188 offset:1920
	ds_write_b16 v182, v189 offset:2000
	ds_write_b16 v182, v190 offset:2080
	ds_write_b16 v182, v191 offset:2160
	s_branch .Lscan_s3_done
